# odin epilogue fast path for prompt-row tiles of the Q/K segments (no RoPE): bf16 stores staged via LDS strip into dwordx4 row chunks; other tiles use the compiled epilogue
# baseline (speedup 1.0000x reference)
.Lodin4_next:
	s_add_i32 s74, s74, s92
	s_cmpk_gt_i32 s74, 0x8ff
	s_cbranch_scc1 .LBB0_1726

.LBB0_1518:
	s_cmp_ge_u32 s11, 0x2000
	s_cbranch_scc1 .Lodin4_old
	s_lshr_b32 s12, s10, 10
	s_cmp_ge_u32 s12, 2
	s_cbranch_scc1 .Lodin4_old
	v_lshl_or_b32 v116, v183, 3, v191
	v_lshrrev_b32_e32 v117, 6, v116
	v_and_b32_e32 v118, 63, v116
	v_lshlrev_b32_e32 v113, 11, v117
	v_add_u32_e32 v113, 0x10000, v113
	v_readfirstlane_b32 s6, v117
	v_and_b32_e32 v116, 31, v118
	v_lshl_add_u32 v112, v116, 1, v113
	v_lshrrev_b32_e32 v117, 5, v118
	v_lshl_add_u32 v112, v117, 8, v112
	v_lshl_add_u32 v113, v118, 4, v113
	v_lshlrev_b32_e32 v115, 2, v116
	v_lshl_add_u32 v115, v117, 14, v115
	v_lshrrev_b32_e32 v117, 2, v118
	v_and_b32_e32 v114, 3, v118
	v_lshlrev_b32_e32 v114, 4, v114
	v_lshl_add_u32 v114, v117, 11, v114
	s_lshr_b32 s7, s6, 1
	s_lshl_b32 s7, s7, 6
	s_add_u32 s7, s7, s11
	s_and_b32 s6, s6, 1
	s_lshl_b32 s6, s6, 6
	s_and_b32 s8, s10, 0x3ff
	s_add_u32 s6, s6, s8
	s_cmp_lg_u32 s12, 0
	s_cbranch_scc1 .Lodin4_kseg
	v_mul_f32_e32 v48, 0x3e38aa3b, v48
	v_mul_f32_e32 v49, 0x3e38aa3b, v49
	v_mul_f32_e32 v50, 0x3e38aa3b, v50
	v_mul_f32_e32 v51, 0x3e38aa3b, v51
	v_mul_f32_e32 v52, 0x3e38aa3b, v52
	v_mul_f32_e32 v53, 0x3e38aa3b, v53
	v_mul_f32_e32 v54, 0x3e38aa3b, v54
	v_mul_f32_e32 v55, 0x3e38aa3b, v55
	v_mul_f32_e32 v56, 0x3e38aa3b, v56
	v_mul_f32_e32 v57, 0x3e38aa3b, v57
	v_mul_f32_e32 v58, 0x3e38aa3b, v58
	v_mul_f32_e32 v59, 0x3e38aa3b, v59
	v_mul_f32_e32 v60, 0x3e38aa3b, v60
	v_mul_f32_e32 v61, 0x3e38aa3b, v61
	v_mul_f32_e32 v62, 0x3e38aa3b, v62
	v_mul_f32_e32 v63, 0x3e38aa3b, v63
	v_mul_f32_e32 v16, 0x3e38aa3b, v16
	v_mul_f32_e32 v17, 0x3e38aa3b, v17
	v_mul_f32_e32 v18, 0x3e38aa3b, v18
	v_mul_f32_e32 v19, 0x3e38aa3b, v19
	v_mul_f32_e32 v20, 0x3e38aa3b, v20
	v_mul_f32_e32 v21, 0x3e38aa3b, v21
	v_mul_f32_e32 v22, 0x3e38aa3b, v22
	v_mul_f32_e32 v23, 0x3e38aa3b, v23
	v_mul_f32_e32 v24, 0x3e38aa3b, v24
	v_mul_f32_e32 v25, 0x3e38aa3b, v25
	v_mul_f32_e32 v26, 0x3e38aa3b, v26
	v_mul_f32_e32 v27, 0x3e38aa3b, v27
	v_mul_f32_e32 v28, 0x3e38aa3b, v28
	v_mul_f32_e32 v29, 0x3e38aa3b, v29
	v_mul_f32_e32 v30, 0x3e38aa3b, v30
	v_mul_f32_e32 v31, 0x3e38aa3b, v31
	v_mul_f32_e32 v32, 0x3e38aa3b, v32
	v_mul_f32_e32 v33, 0x3e38aa3b, v33
	v_mul_f32_e32 v34, 0x3e38aa3b, v34
	v_mul_f32_e32 v35, 0x3e38aa3b, v35
	v_mul_f32_e32 v36, 0x3e38aa3b, v36
	v_mul_f32_e32 v37, 0x3e38aa3b, v37
	v_mul_f32_e32 v38, 0x3e38aa3b, v38
	v_mul_f32_e32 v39, 0x3e38aa3b, v39
	v_mul_f32_e32 v40, 0x3e38aa3b, v40
	v_mul_f32_e32 v41, 0x3e38aa3b, v41
	v_mul_f32_e32 v42, 0x3e38aa3b, v42
	v_mul_f32_e32 v43, 0x3e38aa3b, v43
	v_mul_f32_e32 v44, 0x3e38aa3b, v44
	v_mul_f32_e32 v45, 0x3e38aa3b, v45
	v_mul_f32_e32 v46, 0x3e38aa3b, v46
	v_mul_f32_e32 v47, 0x3e38aa3b, v47
	v_mul_f32_e32 v0, 0x3e38aa3b, v0
	v_mul_f32_e32 v1, 0x3e38aa3b, v1
	v_mul_f32_e32 v2, 0x3e38aa3b, v2
	v_mul_f32_e32 v3, 0x3e38aa3b, v3
	v_mul_f32_e32 v4, 0x3e38aa3b, v4
	v_mul_f32_e32 v5, 0x3e38aa3b, v5
	v_mul_f32_e32 v6, 0x3e38aa3b, v6
	v_mul_f32_e32 v7, 0x3e38aa3b, v7
	v_mul_f32_e32 v8, 0x3e38aa3b, v8
	v_mul_f32_e32 v9, 0x3e38aa3b, v9
	v_mul_f32_e32 v10, 0x3e38aa3b, v10
	v_mul_f32_e32 v11, 0x3e38aa3b, v11
	v_mul_f32_e32 v12, 0x3e38aa3b, v12
	v_mul_f32_e32 v13, 0x3e38aa3b, v13
	v_mul_f32_e32 v14, 0x3e38aa3b, v14
	v_mul_f32_e32 v15, 0x3e38aa3b, v15
	s_mov_b32 s9, 0x3971900
	s_branch .Lodin4_nat
.Lodin4_kseg:
	s_lshl_b32 s8, s7, 12
	s_lshl_b32 s9, s6, 2
	s_add_u32 s8, s8, s9
	s_add_u32 s8, s8, 0x3000000
	s_add_u32 s98, s88, s8
	s_addc_u32 s99, s89, 0
	global_store_dword v115, v48, s[98:99]
	global_store_dword v115, v16, s[98:99] offset:128
	s_add_u32 s98, s98, 0x1000
	s_addc_u32 s99, s99, 0
	global_store_dword v115, v49, s[98:99]
	global_store_dword v115, v17, s[98:99] offset:128
	s_add_u32 s98, s98, 0x1000
	s_addc_u32 s99, s99, 0
	global_store_dword v115, v50, s[98:99]
	global_store_dword v115, v18, s[98:99] offset:128
	s_add_u32 s98, s98, 0x1000
	s_addc_u32 s99, s99, 0
	global_store_dword v115, v51, s[98:99]
	global_store_dword v115, v19, s[98:99] offset:128
	s_add_u32 s98, s98, 0x5000
	s_addc_u32 s99, s99, 0
	global_store_dword v115, v52, s[98:99]
	global_store_dword v115, v20, s[98:99] offset:128
	s_add_u32 s98, s98, 0x1000
	s_addc_u32 s99, s99, 0
	global_store_dword v115, v53, s[98:99]
	global_store_dword v115, v21, s[98:99] offset:128
	s_add_u32 s98, s98, 0x1000
	s_addc_u32 s99, s99, 0
	global_store_dword v115, v54, s[98:99]
	global_store_dword v115, v22, s[98:99] offset:128
	s_add_u32 s98, s98, 0x1000
	s_addc_u32 s99, s99, 0
	global_store_dword v115, v55, s[98:99]
	global_store_dword v115, v23, s[98:99] offset:128
	s_add_u32 s98, s98, 0x5000
	s_addc_u32 s99, s99, 0
	global_store_dword v115, v56, s[98:99]
	global_store_dword v115, v24, s[98:99] offset:128
	s_add_u32 s98, s98, 0x1000
	s_addc_u32 s99, s99, 0
	global_store_dword v115, v57, s[98:99]
	global_store_dword v115, v25, s[98:99] offset:128
	s_add_u32 s98, s98, 0x1000
	s_addc_u32 s99, s99, 0
	global_store_dword v115, v58, s[98:99]
	global_store_dword v115, v26, s[98:99] offset:128
	s_add_u32 s98, s98, 0x1000
	s_addc_u32 s99, s99, 0
	global_store_dword v115, v59, s[98:99]
	global_store_dword v115, v27, s[98:99] offset:128
	s_add_u32 s98, s98, 0x5000
	s_addc_u32 s99, s99, 0
	global_store_dword v115, v60, s[98:99]
	global_store_dword v115, v28, s[98:99] offset:128
	s_add_u32 s98, s98, 0x1000
	s_addc_u32 s99, s99, 0
	global_store_dword v115, v61, s[98:99]
	global_store_dword v115, v29, s[98:99] offset:128
	s_add_u32 s98, s98, 0x1000
	s_addc_u32 s99, s99, 0
	global_store_dword v115, v62, s[98:99]
	global_store_dword v115, v30, s[98:99] offset:128
	s_add_u32 s98, s98, 0x1000
	s_addc_u32 s99, s99, 0
	global_store_dword v115, v63, s[98:99]
	global_store_dword v115, v31, s[98:99] offset:128
	s_add_u32 s98, s98, 0x5000
	s_addc_u32 s99, s99, 0
	global_store_dword v115, v32, s[98:99]
	global_store_dword v115, v0, s[98:99] offset:128
	s_add_u32 s98, s98, 0x1000
	s_addc_u32 s99, s99, 0
	global_store_dword v115, v33, s[98:99]
	global_store_dword v115, v1, s[98:99] offset:128
	s_add_u32 s98, s98, 0x1000
	s_addc_u32 s99, s99, 0
	global_store_dword v115, v34, s[98:99]
	global_store_dword v115, v2, s[98:99] offset:128
	s_add_u32 s98, s98, 0x1000
	s_addc_u32 s99, s99, 0
	global_store_dword v115, v35, s[98:99]
	global_store_dword v115, v3, s[98:99] offset:128
	s_add_u32 s98, s98, 0x5000
	s_addc_u32 s99, s99, 0
	global_store_dword v115, v36, s[98:99]
	global_store_dword v115, v4, s[98:99] offset:128
	s_add_u32 s98, s98, 0x1000
	s_addc_u32 s99, s99, 0
	global_store_dword v115, v37, s[98:99]
	global_store_dword v115, v5, s[98:99] offset:128
	s_add_u32 s98, s98, 0x1000
	s_addc_u32 s99, s99, 0
	global_store_dword v115, v38, s[98:99]
	global_store_dword v115, v6, s[98:99] offset:128
	s_add_u32 s98, s98, 0x1000
	s_addc_u32 s99, s99, 0
	global_store_dword v115, v39, s[98:99]
	global_store_dword v115, v7, s[98:99] offset:128
	s_add_u32 s98, s98, 0x5000
	s_addc_u32 s99, s99, 0
	global_store_dword v115, v40, s[98:99]
	global_store_dword v115, v8, s[98:99] offset:128
	s_add_u32 s98, s98, 0x1000
	s_addc_u32 s99, s99, 0
	global_store_dword v115, v41, s[98:99]
	global_store_dword v115, v9, s[98:99] offset:128
	s_add_u32 s98, s98, 0x1000
	s_addc_u32 s99, s99, 0
	global_store_dword v115, v42, s[98:99]
	global_store_dword v115, v10, s[98:99] offset:128
	s_add_u32 s98, s98, 0x1000
	s_addc_u32 s99, s99, 0
	global_store_dword v115, v43, s[98:99]
	global_store_dword v115, v11, s[98:99] offset:128
	s_add_u32 s98, s98, 0x5000
	s_addc_u32 s99, s99, 0
	global_store_dword v115, v44, s[98:99]
	global_store_dword v115, v12, s[98:99] offset:128
	s_add_u32 s98, s98, 0x1000
	s_addc_u32 s99, s99, 0
	global_store_dword v115, v45, s[98:99]
	global_store_dword v115, v13, s[98:99] offset:128
	s_add_u32 s98, s98, 0x1000
	s_addc_u32 s99, s99, 0
	global_store_dword v115, v46, s[98:99]
	global_store_dword v115, v14, s[98:99] offset:128
	s_add_u32 s98, s98, 0x1000
	s_addc_u32 s99, s99, 0
	global_store_dword v115, v47, s[98:99]
	global_store_dword v115, v15, s[98:99] offset:128
	s_mov_b32 s9, 0x5171900
.Lodin4_nat:
	s_lshl_b32 s8, s7, 11
	s_add_u32 s8, s8, s9
	s_lshl_b32 s9, s6, 1
	s_add_u32 s8, s8, s9
	s_add_u32 s98, s90, s8
	s_addc_u32 s99, s91, 0
	v_cvt_pk_bf16_f32 v64, v48, v49
	v_cvt_pk_bf16_f32 v65, v50, v51
	v_cvt_pk_bf16_f32 v66, v52, v53
	v_cvt_pk_bf16_f32 v67, v54, v55
	v_cvt_pk_bf16_f32 v68, v56, v57
	v_cvt_pk_bf16_f32 v69, v58, v59
	v_cvt_pk_bf16_f32 v70, v60, v61
	v_cvt_pk_bf16_f32 v71, v62, v63
	ds_write_b16 v112, v64
	ds_write_b16_d16_hi v112, v64 offset:64
	ds_write_b16 v112, v65 offset:128
	ds_write_b16_d16_hi v112, v65 offset:192
	ds_write_b16 v112, v66 offset:512
	ds_write_b16_d16_hi v112, v66 offset:576
	ds_write_b16 v112, v67 offset:640
	ds_write_b16_d16_hi v112, v67 offset:704
	ds_write_b16 v112, v68 offset:1024
	ds_write_b16_d16_hi v112, v68 offset:1088
	ds_write_b16 v112, v69 offset:1152
	ds_write_b16_d16_hi v112, v69 offset:1216
	ds_write_b16 v112, v70 offset:1536
	ds_write_b16_d16_hi v112, v70 offset:1600
	ds_write_b16 v112, v71 offset:1664
	ds_write_b16_d16_hi v112, v71 offset:1728
	ds_read_b128 v[120:123], v113
	ds_read_b128 v[124:127], v113 offset:1024
	s_waitcnt lgkmcnt(0)
	global_store_dwordx4 v114, v[120:123], s[98:99]
	s_add_u32 s100, s98, 0x8000
	s_addc_u32 s101, s99, 0
	global_store_dwordx4 v114, v[124:127], s[100:101]
	v_cvt_pk_bf16_f32 v72, v16, v17
	v_cvt_pk_bf16_f32 v73, v18, v19
	v_cvt_pk_bf16_f32 v74, v20, v21
	v_cvt_pk_bf16_f32 v75, v22, v23
	v_cvt_pk_bf16_f32 v76, v24, v25
	v_cvt_pk_bf16_f32 v77, v26, v27
	v_cvt_pk_bf16_f32 v78, v28, v29
	v_cvt_pk_bf16_f32 v79, v30, v31
	ds_write_b16 v112, v72
	ds_write_b16_d16_hi v112, v72 offset:64
	ds_write_b16 v112, v73 offset:128
	ds_write_b16_d16_hi v112, v73 offset:192
	ds_write_b16 v112, v74 offset:512
	ds_write_b16_d16_hi v112, v74 offset:576
	ds_write_b16 v112, v75 offset:640
	ds_write_b16_d16_hi v112, v75 offset:704
	ds_write_b16 v112, v76 offset:1024
	ds_write_b16_d16_hi v112, v76 offset:1088
	ds_write_b16 v112, v77 offset:1152
	ds_write_b16_d16_hi v112, v77 offset:1216
	ds_write_b16 v112, v78 offset:1536
	ds_write_b16_d16_hi v112, v78 offset:1600
	ds_write_b16 v112, v79 offset:1664
	ds_write_b16_d16_hi v112, v79 offset:1728
	ds_read_b128 v[120:123], v113
	ds_read_b128 v[124:127], v113 offset:1024
	s_waitcnt lgkmcnt(0)
	global_store_dwordx4 v114, v[120:123], s[98:99] offset:64
	global_store_dwordx4 v114, v[124:127], s[100:101] offset:64
	s_add_u32 s98, s98, 0x10000
	s_addc_u32 s99, s99, 0
	v_cvt_pk_bf16_f32 v64, v32, v33
	v_cvt_pk_bf16_f32 v65, v34, v35
	v_cvt_pk_bf16_f32 v66, v36, v37
	v_cvt_pk_bf16_f32 v67, v38, v39
	v_cvt_pk_bf16_f32 v68, v40, v41
	v_cvt_pk_bf16_f32 v69, v42, v43
	v_cvt_pk_bf16_f32 v70, v44, v45
	v_cvt_pk_bf16_f32 v71, v46, v47
	ds_write_b16 v112, v64
	ds_write_b16_d16_hi v112, v64 offset:64
	ds_write_b16 v112, v65 offset:128
	ds_write_b16_d16_hi v112, v65 offset:192
	ds_write_b16 v112, v66 offset:512
	ds_write_b16_d16_hi v112, v66 offset:576
	ds_write_b16 v112, v67 offset:640
	ds_write_b16_d16_hi v112, v67 offset:704
	ds_write_b16 v112, v68 offset:1024
	ds_write_b16_d16_hi v112, v68 offset:1088
	ds_write_b16 v112, v69 offset:1152
	ds_write_b16_d16_hi v112, v69 offset:1216
	ds_write_b16 v112, v70 offset:1536
	ds_write_b16_d16_hi v112, v70 offset:1600
	ds_write_b16 v112, v71 offset:1664
	ds_write_b16_d16_hi v112, v71 offset:1728
	ds_read_b128 v[120:123], v113
	ds_read_b128 v[124:127], v113 offset:1024
	s_waitcnt lgkmcnt(0)
	global_store_dwordx4 v114, v[120:123], s[98:99]
	s_add_u32 s100, s98, 0x8000
	s_addc_u32 s101, s99, 0
	global_store_dwordx4 v114, v[124:127], s[100:101]
	v_cvt_pk_bf16_f32 v72, v0, v1
	v_cvt_pk_bf16_f32 v73, v2, v3
	v_cvt_pk_bf16_f32 v74, v4, v5
	v_cvt_pk_bf16_f32 v75, v6, v7
	v_cvt_pk_bf16_f32 v76, v8, v9
	v_cvt_pk_bf16_f32 v77, v10, v11
	v_cvt_pk_bf16_f32 v78, v12, v13
	v_cvt_pk_bf16_f32 v79, v14, v15
	ds_write_b16 v112, v72
	ds_write_b16_d16_hi v112, v72 offset:64
	ds_write_b16 v112, v73 offset:128
	ds_write_b16_d16_hi v112, v73 offset:192
	ds_write_b16 v112, v74 offset:512
	ds_write_b16_d16_hi v112, v74 offset:576
	ds_write_b16 v112, v75 offset:640
	ds_write_b16_d16_hi v112, v75 offset:704
	ds_write_b16 v112, v76 offset:1024
	ds_write_b16_d16_hi v112, v76 offset:1088
	ds_write_b16 v112, v77 offset:1152
	ds_write_b16_d16_hi v112, v77 offset:1216
	ds_write_b16 v112, v78 offset:1536
	ds_write_b16_d16_hi v112, v78 offset:1600
	ds_write_b16 v112, v79 offset:1664
	ds_write_b16_d16_hi v112, v79 offset:1728
	ds_read_b128 v[120:123], v113
	ds_read_b128 v[124:127], v113 offset:1024
	s_waitcnt lgkmcnt(0)
	global_store_dwordx4 v114, v[120:123], s[98:99] offset:64
	global_store_dwordx4 v114, v[124:127], s[100:101] offset:64
	s_branch .Lodin4_next
